# deferred-work publish counter checked by the barrier leader together with the barrier poll (one load per workgroup) instead of by all waves at P3 entry
# speedup vs baseline: 1.0451x; 1.0097x over previous
; __device__ __forceinline__ void xcd_local_bar(unsigned* ctr, unsigned target, bool leader) {
;     asm volatile("s_waitcnt vmcnt(0) lgkmcnt(0)" ::: "memory");
;     __syncthreads();
;     if (leader) {
;         __hip_atomic_fetch_add(ctr, 1u, __ATOMIC_RELAXED, __HIP_MEMORY_SCOPE_AGENT);
;         while (__hip_atomic_load(ctr, __ATOMIC_RELAXED, __HIP_MEMORY_SCOPE_AGENT) < target) __builtin_amdgcn_s_sleep(1);
;         __builtin_amdgcn_fence(__ATOMIC_ACQUIRE, "agent");
;         asm volatile("s_waitcnt vmcnt(0)" ::: "memory");
.LBB0_484:
	s_or_b64 exec, exec, s[26:27]
	buffer_inv sc1
	v_mov_b32_e32 v0, 0
	v_mov_b32_e32 v2, -1
	s_cmp_lg_u32 s20, 0x100
	s_cbranch_scc1 .Lrd2_noload
	global_load_dword v2, v0, s[18:19] offset:2816 sc1
.Lrd2_noload:
	global_load_dword v1, v0, s[10:11] offset:256 sc1
	s_waitcnt vmcnt(0)
	v_cmp_le_u32_e32 vcc, s24, v1
	s_cbranch_vccnz .LBB0_486

; __device__ __forceinline__ void xcd_local_bar(unsigned* ctr, unsigned target, bool leader) {
;     ...
;     if (leader) {
;         __hip_atomic_fetch_add(ctr, 1u, __ATOMIC_RELAXED, __HIP_MEMORY_SCOPE_AGENT);
;         while (__hip_atomic_load(ctr, __ATOMIC_RELAXED, __HIP_MEMORY_SCOPE_AGENT) < target) __builtin_amdgcn_s_sleep(1);
;         __builtin_amdgcn_fence(__ATOMIC_ACQUIRE, "agent");
;         asm volatile("s_waitcnt vmcnt(0)" ::: "memory");
.Lrd2_poll:
	v_cmp_le_u32_e32 vcc, 0xc0, v2
	s_cbranch_vccnz .Lrd2_ok
	s_sleep 2
	global_load_dword v2, v0, s[18:19] offset:2816 sc1
	s_waitcnt vmcnt(0)
	s_branch .Lrd2_poll

; __device__ __forceinline__ void xcd_local_bar(unsigned* ctr, unsigned target, bool leader) {
;     ...
;         asm volatile("s_waitcnt vmcnt(0)" ::: "memory");
;     }
;     __syncthreads();
.LBB0_496:
	s_or_b64 exec, exec, s[10:11]
	s_barrier
	s_cmp_lg_u32 s20, 0x100
	s_cbranch_scc1 .Lrd_skip
	v_mov_b32_e32 v0, 0

; __device__ __forceinline__ void xcd_local_bar(unsigned* ctr, unsigned target, bool leader) {
;     ...
;         asm volatile("s_waitcnt vmcnt(0)" ::: "memory");
;     }
;     __syncthreads();
.Lrd_ok:
	buffer_inv sc1
	s_waitcnt vmcnt(0)
.Lrd_skip:
	s_branch .LBB0_499
.LBB0_497:
	v_readlane_b32 s94, v248, 2
	s_mov_b32 s93, s69
	v_readlane_b32 s95, v248, 3
	s_cbranch_execnz .LBB0_488
